# speedup vs baseline: 1.0070x; 1.0070x over previous
; DI void cmp_item(const u16* R, const u16* kc, const u16* vct, float* Oc, float* impH, float* linv, int hh, int qtile, float kcmax2, int part, float* lds) {
;     ...
;       f32x16 s = qk_tile(cur, q);
;       const int nb = n0 + 8 * h2;
;       float p[16];
; #pragma unroll
;       for (int i = 0; i < 16; ++i) {
;         const int c = nb + (i & 7) + 16 * (i >> 3);
;         const bool valid = (16 * c + 31) <= tq;
;         p[i] = valid ? __expf(s[i] - slope * ((float)(tq - 16 * c) - 15.5f) - mshift) : 0.f;
;       }
.LBB0_875:
	s_or_b64 exec, exec, s[52:53]
	v_mfma_f32_32x32x16_bf16 v[34:49], v[34:37], v[50:53], 0
	v_add_u32_e32 v0, 0xffffff10, v147
	v_cmp_le_i32_e64 s[46:47], v0, v126
	v_mfma_f32_32x32x16_bf16 v[34:49], v[114:117], v[54:57], v[34:49]
	v_mov_b32_e32 v114, 0
	v_mov_b32_e32 v116, 0
	v_mfma_f32_32x32x16_bf16 v[34:49], v[122:125], v[58:61], v[34:49]
	v_mfma_f32_32x32x16_bf16 v[34:49], v[118:121], v[62:65], v[34:49]
	s_and_saveexec_b64 s[52:53], s[46:47]
	v_add_u32_e32 v0, 0x160, v146
	v_cvt_f32_i32_e32 v0, v0
	v_add_f32_e32 v0, 0xc1780000, v0
	s_nop 6
	v_fma_f32 v0, -v140, v0, v35
	v_sub_f32_e32 v0, v0, v141
	v_mul_f32_e32 v0, 0x3fb8aa3b, v0
	v_exp_f32_e32 v116, v0
.LBB0_877:
	s_or_b64 exec, exec, s[52:53]
	v_add_u32_e32 v0, 0xffffff20, v147
	v_cmp_le_i32_e64 s[46:47], v0, v126
	v_mov_b32_e32 v118, 0
	s_and_saveexec_b64 s[52:53], s[46:47]
	v_add_u32_e32 v0, 0x150, v146
	v_cvt_f32_i32_e32 v0, v0
	v_add_f32_e32 v0, 0xc1780000, v0
	s_nop 0
	v_fma_f32 v0, -v140, v0, v36
	v_sub_f32_e32 v0, v0, v141
	v_mul_f32_e32 v0, 0x3fb8aa3b, v0
	v_exp_f32_e32 v118, v0
.LBB0_879:
	s_or_b64 exec, exec, s[52:53]
	v_add_u32_e32 v0, 0xffffff30, v147
	v_cmp_le_i32_e64 s[46:47], v0, v126
	s_and_saveexec_b64 s[52:53], s[46:47]
	v_add_u32_e32 v0, 0x140, v146
	v_cvt_f32_i32_e32 v0, v0
	v_add_f32_e32 v0, 0xc1780000, v0
	v_fma_f32 v0, -v140, v0, v37
	v_sub_f32_e32 v0, v0, v141
	v_mul_f32_e32 v0, 0x3fb8aa3b, v0
	v_exp_f32_e32 v114, v0
.LBB0_881:
	s_or_b64 exec, exec, s[52:53]
	v_add_u32_e32 v0, 0xffffff40, v147
	v_cmp_le_i32_e64 s[46:47], v0, v126
	v_mov_b32_e32 v36, 0
	v_mov_b32_e32 v120, 0
	s_and_saveexec_b64 s[52:53], s[46:47]
	v_add_u32_e32 v0, 0x130, v146
	v_cvt_f32_i32_e32 v0, v0
	v_add_f32_e32 v0, 0xc1780000, v0
	v_fma_f32 v0, -v140, v0, v38
	v_sub_f32_e32 v0, v0, v141
	v_mul_f32_e32 v0, 0x3fb8aa3b, v0
	v_exp_f32_e32 v120, v0
.LBB0_883:
	s_or_b64 exec, exec, s[52:53]
	v_add_u32_e32 v0, 0xffffff50, v147
	v_cmp_le_i32_e64 s[46:47], v0, v126
	s_and_saveexec_b64 s[52:53], s[46:47]
	v_add_u32_e32 v0, 0x120, v146
	v_cvt_f32_i32_e32 v0, v0
	v_add_f32_e32 v0, 0xc1780000, v0
	v_fma_f32 v0, -v140, v0, v39
	v_sub_f32_e32 v0, v0, v141
	v_mul_f32_e32 v0, 0x3fb8aa3b, v0
	v_exp_f32_e32 v36, v0
.LBB0_885:
	s_or_b64 exec, exec, s[52:53]
	v_add_u32_e32 v0, 0xffffff60, v147
	v_cmp_le_i32_e64 s[46:47], v0, v126
	v_mov_b32_e32 v38, 0
	v_mov_b32_e32 v122, 0
	s_and_saveexec_b64 s[52:53], s[46:47]
	v_add_u32_e32 v0, 0x110, v146
	v_cvt_f32_i32_e32 v0, v0
	v_add_f32_e32 v0, 0xc1780000, v0
	v_fma_f32 v0, -v140, v0, v40
	v_sub_f32_e32 v0, v0, v141
	v_mul_f32_e32 v0, 0x3fb8aa3b, v0
	v_exp_f32_e32 v122, v0
.LBB0_887:
	s_or_b64 exec, exec, s[52:53]
	v_add_u32_e32 v0, 0xffffff70, v147
	v_cmp_le_i32_e64 s[46:47], v0, v126
	s_and_saveexec_b64 s[52:53], s[46:47]
	v_add_u32_e32 v0, 0x100, v146
	v_cvt_f32_i32_e32 v0, v0
	v_add_f32_e32 v0, 0xc1780000, v0
	v_fma_f32 v0, -v140, v0, v41
	v_sub_f32_e32 v0, v0, v141
	v_mul_f32_e32 v0, 0x3fb8aa3b, v0
	v_exp_f32_e32 v38, v0
.LBB0_889:
	s_or_b64 exec, exec, s[52:53]
	v_cmp_le_i32_e64 s[46:47], v147, v126
	v_mov_b32_e32 v117, 0
	v_mov_b32_e32 v35, 0
	s_and_saveexec_b64 s[52:53], s[46:47]
	v_add_u32_e32 v0, 0x70, v146
	v_cvt_f32_i32_e32 v0, v0
	v_add_f32_e32 v0, 0xc1780000, v0
	v_fma_f32 v0, -v140, v0, v42
	v_sub_f32_e32 v0, v0, v141
	v_mul_f32_e32 v0, 0x3fb8aa3b, v0
	v_exp_f32_e32 v35, v0
.LBB0_891:
	s_or_b64 exec, exec, s[52:53]
	v_add_u32_e32 v0, 16, v147
	v_cmp_le_i32_e64 s[46:47], v0, v126
	s_and_saveexec_b64 s[52:53], s[46:47]
	v_add_u32_e32 v0, 0x60, v146
	v_cvt_f32_i32_e32 v0, v0
	v_add_f32_e32 v0, 0xc1780000, v0
	v_fma_f32 v0, -v140, v0, v43
	v_sub_f32_e32 v0, v0, v141
	v_mul_f32_e32 v0, 0x3fb8aa3b, v0
	v_exp_f32_e32 v117, v0
.LBB0_893:
	s_or_b64 exec, exec, s[52:53]
	v_add_u32_e32 v0, 32, v147
	v_cmp_le_i32_e64 s[46:47], v0, v126
	v_mov_b32_e32 v115, 0
	v_mov_b32_e32 v119, 0
	s_and_saveexec_b64 s[52:53], s[46:47]
	v_add_u32_e32 v0, 0x50, v146
	v_cvt_f32_i32_e32 v0, v0
	v_add_f32_e32 v0, 0xc1780000, v0
	v_fma_f32 v0, -v140, v0, v44
	v_sub_f32_e32 v0, v0, v141
	v_mul_f32_e32 v0, 0x3fb8aa3b, v0
	v_exp_f32_e32 v119, v0
.LBB0_895:
	s_or_b64 exec, exec, s[52:53]
	v_add_u32_e32 v0, 48, v147
	v_cmp_le_i32_e64 s[46:47], v0, v126
	s_and_saveexec_b64 s[52:53], s[46:47]
	v_add_u32_e32 v0, 64, v146
	v_cvt_f32_i32_e32 v0, v0
	v_add_f32_e32 v0, 0xc1780000, v0
	v_fma_f32 v0, -v140, v0, v45
	v_sub_f32_e32 v0, v0, v141
	v_mul_f32_e32 v0, 0x3fb8aa3b, v0
	v_exp_f32_e32 v115, v0
.LBB0_897:
	s_or_b64 exec, exec, s[52:53]
	v_add_u32_e32 v0, 64, v147
	v_cmp_le_i32_e64 s[46:47], v0, v126
	v_mov_b32_e32 v37, 0
	v_mov_b32_e32 v121, 0
	s_and_saveexec_b64 s[52:53], s[46:47]
	v_add_u32_e32 v0, 48, v146
	v_cvt_f32_i32_e32 v0, v0
	v_add_f32_e32 v0, 0xc1780000, v0
	v_fma_f32 v0, -v140, v0, v46
	v_sub_f32_e32 v0, v0, v141
	v_mul_f32_e32 v0, 0x3fb8aa3b, v0
	v_exp_f32_e32 v121, v0
.LBB0_899:
	s_or_b64 exec, exec, s[52:53]
	v_add_u32_e32 v0, 0x50, v147
	v_cmp_le_i32_e64 s[46:47], v0, v126
	s_and_saveexec_b64 s[52:53], s[46:47]
	v_add_u32_e32 v0, 32, v146
	v_cvt_f32_i32_e32 v0, v0
	v_add_f32_e32 v0, 0xc1780000, v0
	v_fma_f32 v0, -v140, v0, v47
	v_sub_f32_e32 v0, v0, v141
	v_mul_f32_e32 v0, 0x3fb8aa3b, v0
	v_exp_f32_e32 v37, v0
.LBB0_901:
	s_or_b64 exec, exec, s[52:53]
	v_add_u32_e32 v0, 0x60, v147
	v_cmp_le_i32_e64 s[46:47], v0, v126
	v_mov_b32_e32 v39, 0
	v_mov_b32_e32 v123, 0
	s_and_saveexec_b64 s[52:53], s[46:47]
	v_add_u32_e32 v0, 16, v146
	v_cvt_f32_i32_e32 v0, v0
	v_add_f32_e32 v0, 0xc1780000, v0
	v_fma_f32 v0, -v140, v0, v48
	v_sub_f32_e32 v0, v0, v141
	v_mul_f32_e32 v0, 0x3fb8aa3b, v0
	v_exp_f32_e32 v123, v0
